# attention loop: removed 70 redundant VALU ops (NaN-canonicalising v_max x,x and 0+x seeds) via copy propagation, on top of v30
# speedup vs baseline: 1.0052x; 1.0003x over previous
.LBB0_157:
	s_nop 1
	v_max_f32_e32 v0, v176, v177
	v_max_f32_e32 v136, v178, v179
	v_max_f32_e32 v137, v182, v183
	v_max3_f32 v137, v180, v181, v137
	v_max3_f32 v0, v0, v136, v137
	ds_bpermute_b32 v136, v199, v0
	s_waitcnt lgkmcnt(0)
	v_max_f32_e32 v0, v0, v136
	ds_bpermute_b32 v136, v195, v0
	s_add_i32 s45, s38, 2
	s_cmp_ge_u32 s45, s36
	s_cselect_b64 s[96:97], -1, 0
	s_waitcnt lgkmcnt(0)
	v_max3_f32 v206, v194, v0, v136
	v_sub_f32_e32 v136, v176, v206
	v_sub_f32_e32 v137, v177, v206
	v_sub_f32_e32 v0, v194, v206
	v_exp_f32_e32 v176, v136
	v_exp_f32_e32 v177, v137
	v_sub_f32_e32 v136, v178, v206
	v_sub_f32_e32 v137, v179, v206
	v_exp_f32_e32 v194, v0
	v_exp_f32_e32 v178, v136
	v_exp_f32_e32 v179, v137
	v_sub_f32_e32 v136, v180, v206
	v_sub_f32_e32 v137, v181, v206
	v_mul_f32_e32 v130, v130, v194
	v_mul_f32_e32 v131, v131, v194
	v_exp_f32_e32 v180, v136
	v_exp_f32_e32 v181, v137
	v_sub_f32_e32 v136, v182, v206
	v_sub_f32_e32 v137, v183, v206
	v_exp_f32_e32 v182, v136
	v_max_f32_e32 v136, v168, v169
	v_max_f32_e32 v138, v170, v171
	v_max_f32_e32 v139, v174, v175
	v_max3_f32 v139, v172, v173, v139
	v_max3_f32 v138, v136, v138, v139
	ds_bpermute_b32 v139, v199, v138
	v_mul_f32_e32 v128, v128, v194
	v_mul_f32_e32 v129, v129, v194
	v_exp_f32_e32 v183, v137
	v_cvt_pk_bf16_f32 v136, v176, v177
	v_cvt_pk_bf16_f32 v137, v178, v179
	s_waitcnt lgkmcnt(0)
	v_max_f32_e32 v0, v138, v139
	ds_bpermute_b32 v197, v195, v0
	v_cvt_pk_bf16_f32 v138, v180, v181
	v_cvt_pk_bf16_f32 v139, v182, v183
	s_cmp_lt_u32 s45, s36
	s_nop 0
	v_mfma_f32_16x16x32_bf16 v[128:131], v[84:87], v[136:139], v[128:131]
	s_waitcnt lgkmcnt(0)
	v_max3_f32 v204, v196, v0, v197
	v_sub_f32_e32 v0, v196, v204
	v_max_f32_e32 v196, v164, v165
	v_max_f32_e32 v197, v166, v167
	v_max_f32_e32 v200, v146, v147
	v_max3_f32 v200, v144, v145, v200
	v_max3_f32 v197, v196, v197, v200
	ds_bpermute_b32 v200, v199, v197
	v_exp_f32_e32 v196, v0
	v_sub_f32_e32 v168, v168, v204
	v_sub_f32_e32 v169, v169, v204
	v_sub_f32_e32 v170, v170, v204
	v_sub_f32_e32 v171, v171, v204
	s_waitcnt lgkmcnt(0)
	v_max_f32_e32 v0, v197, v200
	ds_bpermute_b32 v197, v195, v0
	v_sub_f32_e32 v172, v172, v204
	v_sub_f32_e32 v173, v173, v204
	v_sub_f32_e32 v174, v174, v204
	v_sub_f32_e32 v175, v175, v204
	v_exp_f32_e32 v168, v168
	v_exp_f32_e32 v169, v169
	s_waitcnt lgkmcnt(0)
	v_max3_f32 v200, v198, v0, v197
	v_mul_f32_e32 v98, v98, v196
	v_mul_f32_e32 v99, v99, v196
	v_mul_f32_e32 v96, v96, v196
	v_mul_f32_e32 v97, v97, v196
	v_sub_f32_e32 v0, v198, v200
	v_max_f32_e32 v197, v140, v141
	v_max_f32_e32 v198, v142, v143
	v_max_f32_e32 v203, v134, v135
	v_max3_f32 v203, v132, v133, v203
	v_max3_f32 v197, v197, v198, v203
	ds_bpermute_b32 v203, v199, v197
	v_exp_f32_e32 v198, v0
	v_sub_f32_e32 v164, v164, v200
	v_sub_f32_e32 v165, v165, v200
	v_sub_f32_e32 v166, v166, v200
	v_sub_f32_e32 v167, v167, v200
	v_sub_f32_e32 v144, v144, v200
	v_sub_f32_e32 v145, v145, v200
	s_waitcnt lgkmcnt(0)
	v_max_f32_e32 v0, v197, v203
	ds_bpermute_b32 v197, v195, v0
	v_sub_f32_e32 v146, v146, v200
	v_sub_f32_e32 v147, v147, v200
	v_mul_f32_e32 v58, v58, v198
	v_mul_f32_e32 v59, v59, v198
	v_mul_f32_e32 v56, v56, v198
	v_mul_f32_e32 v57, v57, v198
	v_exp_f32_e32 v170, v170
	s_waitcnt lgkmcnt(0)
	v_max3_f32 v0, v202, v0, v197
	v_sub_f32_e32 v197, v202, v0
	v_sub_f32_e32 v134, v134, v0
	v_sub_f32_e32 v135, v135, v0
	v_sub_f32_e32 v140, v140, v0
	v_sub_f32_e32 v141, v141, v0
	v_exp_f32_e32 v202, v134
	v_exp_f32_e32 v134, v197
	v_sub_f32_e32 v142, v142, v0
	v_sub_f32_e32 v143, v143, v0
	v_sub_f32_e32 v132, v132, v0
	v_sub_f32_e32 v133, v133, v0
	v_exp_f32_e32 v171, v171
	v_mul_f32_e32 v6, v6, v134
	v_mul_f32_e32 v7, v7, v134
	v_mul_f32_e32 v4, v4, v134
	v_mul_f32_e32 v5, v5, v134
	v_exp_f32_e32 v172, v172
	v_exp_f32_e32 v173, v173
	v_exp_f32_e32 v174, v174
	v_exp_f32_e32 v175, v175
	v_cvt_pk_bf16_f32 v208, v168, v169
	v_cvt_pk_bf16_f32 v209, v170, v171
	v_cvt_pk_bf16_f32 v210, v172, v173
	v_cvt_pk_bf16_f32 v211, v174, v175
	v_exp_f32_e32 v164, v164
	v_exp_f32_e32 v165, v165
	v_exp_f32_e32 v166, v166
	v_exp_f32_e32 v167, v167
	v_exp_f32_e32 v144, v144
	v_exp_f32_e32 v145, v145
	v_exp_f32_e32 v146, v146
	v_exp_f32_e32 v147, v147
	v_cvt_pk_bf16_f32 v212, v164, v165
	v_cvt_pk_bf16_f32 v213, v166, v167
	v_cvt_pk_bf16_f32 v214, v144, v145
	v_cvt_pk_bf16_f32 v215, v146, v147
	v_exp_f32_e32 v140, v140
	v_exp_f32_e32 v141, v141
	v_exp_f32_e32 v142, v142
	v_exp_f32_e32 v143, v143
	v_exp_f32_e32 v132, v132
	v_exp_f32_e32 v133, v133
	v_exp_f32_e32 v203, v135
	v_mfma_f32_16x16x32_bf16 v[96:99], v[84:87], v[208:211], v[96:99]
	v_cvt_pk_bf16_f32 v240, v140, v141
	v_cvt_pk_bf16_f32 v241, v142, v143
	v_cvt_pk_bf16_f32 v242, v132, v133
	v_mfma_f32_16x16x32_bf16 v[56:59], v[84:87], v[212:215], v[56:59]
	v_cvt_pk_bf16_f32 v243, v202, v203
	v_mul_f32_e64 v82, v82, v196
	v_mul_f32_e64 v83, v83, v196
	v_mul_f32_e32 v80, v80, v196
	v_mul_f32_e32 v81, v81, v196
	v_mfma_f32_16x16x32_bf16 v[4:7], v[84:87], v[240:243], v[4:7]
	v_mul_f32_e64 v86, v118, v194
	v_mul_f32_e64 v87, v119, v194
	v_mul_f32_e32 v84, v116, v194
	v_mul_f32_e32 v85, v117, v194
	v_mul_f32_e32 v54, v54, v198
	v_mul_f32_e32 v55, v55, v198
	v_mul_f32_e32 v52, v52, v198
	v_mul_f32_e32 v53, v53, v198
	v_mul_f32_e32 v10, v10, v134
	v_mul_f32_e32 v11, v11, v134
	v_mul_f32_e32 v8, v8, v134
	v_mul_f32_e32 v9, v9, v134
	v_mfma_f32_16x16x32_bf16 v[116:119], v[76:79], v[136:139], v[84:87]
	v_mul_f32_e64 v62, v62, v198
	v_mul_f32_e64 v63, v63, v198
	v_mul_f32_e32 v60, v60, v198
	v_mul_f32_e32 v61, v61, v198
	v_mul_f32_e32 v14, v14, v134
	v_mul_f32_e32 v15, v15, v134
	v_mfma_f32_16x16x32_bf16 v[80:83], v[76:79], v[208:211], v[80:83]
	v_mul_f32_e64 v12, v12, v134
	v_mul_f32_e64 v13, v13, v134
	v_mul_f32_e32 v66, v66, v198
	v_mul_f32_e32 v67, v67, v198
	v_mul_f32_e32 v64, v64, v198
	v_mul_f32_e32 v65, v65, v198
	v_mfma_f32_16x16x32_bf16 v[52:55], v[76:79], v[212:215], v[52:55]
	v_mul_f32_e64 v18, v18, v134
	v_mul_f32_e64 v19, v19, v134
	v_mul_f32_e32 v16, v16, v134
	v_mul_f32_e32 v17, v17, v134
	s_cselect_b32 s24, s45, s38
	v_mfma_f32_16x16x32_bf16 v[8:11], v[76:79], v[240:243], v[8:11]
	v_mul_f32_e64 v78, v122, v194
	v_mul_f32_e64 v79, v123, v194
	v_mul_f32_e32 v76, v120, v194
	v_mul_f32_e32 v77, v121, v194
	s_cmp_lt_i32 s24, s40
	v_mfma_f32_16x16x32_bf16 v[60:63], v[72:75], v[212:215], v[60:63]
	v_mfma_f32_16x16x32_bf16 v[120:123], v[72:75], v[136:139], v[76:79]
	s_nop 2
	v_mul_f32_e64 v78, v90, v196
	v_mul_f32_e64 v79, v91, v196
	v_mul_f32_e32 v76, v88, v196
	v_mul_f32_e32 v77, v89, v196
	v_mfma_f32_16x16x32_bf16 v[12:15], v[72:75], v[240:243], v[12:15]
	s_nop 0
	v_mfma_f32_16x16x32_bf16 v[88:91], v[72:75], v[208:211], v[76:79]
	v_mul_f32_e64 v74, v126, v194
	v_mul_f32_e64 v75, v127, v194
	v_mul_f32_e32 v72, v124, v194
	v_mul_f32_e32 v73, v125, v194
	v_mfma_f32_16x16x32_bf16 v[64:67], v[68:71], v[212:215], v[64:67]
	s_nop 0
	v_mfma_f32_16x16x32_bf16 v[124:127], v[68:71], v[136:139], v[72:75]
	s_nop 2
	v_mul_f32_e64 v74, v102, v196
	v_mul_f32_e64 v75, v103, v196
	v_mul_f32_e32 v72, v100, v196
	v_mul_f32_e32 v73, v101, v196
	v_mfma_f32_16x16x32_bf16 v[16:19], v[68:71], v[240:243], v[16:19]
	s_nop 0
	v_mfma_f32_16x16x32_bf16 v[100:103], v[68:71], v[208:211], v[72:75]
	s_cbranch_scc1 .LBB0_159
	s_sub_i32 s24, s24, s40
	s_mov_b64 s[6:7], 0x6020
	s_mov_b64 s[8:9], 0x6000
	s_mov_b64 s[10:11], 0x4020
	s_mov_b64 s[12:13], 0x4000
	s_mov_b64 s[16:17], 0x2020
	s_mov_b64 s[18:19], 0x2000
	s_mov_b64 s[22:23], s[84:85]
	s_mov_b64 s[20:21], s[0:1]
	v_mov_b64_e32 v[68:69], v[188:189]
	s_branch .LBB0_160

; __device__ __forceinline__ void attn_item(const Params& p, int l, int hs, int idx) {
;     ...
;         ATT_LOAD(i2, kfa, vla, vha);
.LBB0_160:
	s_lshl_b32 s25, s24, 6
	s_add_u32 s20, s20, s25
	s_addc_u32 s21, s21, 0
	v_add_f32_e32 v70, v178, v176
	v_add_f32_e32 v71, v179, v177
	v_add_f32_e32 v72, v170, v168
	v_add_f32_e32 v73, v171, v169
	s_add_u32 s18, s20, s18
	v_add_f32_e32 v70, v180, v70
	v_add_f32_e32 v71, v181, v71
	v_add_f32_e32 v72, v172, v72
	v_add_f32_e32 v73, v173, v73
	s_addc_u32 s19, s21, s19
	v_add_f32_e32 v70, v182, v70
	v_add_f32_e32 v71, v183, v71
	v_add_f32_e32 v72, v174, v72
	v_add_f32_e32 v73, v175, v73
	s_add_u32 s16, s20, s16
	v_mov_b32_e32 v74, v72
	v_mov_b32_e32 v75, v70
	v_mov_b32_e32 v70, v73
	s_addc_u32 s17, s21, s17
	v_mov_b32_e32 v197, v194
	v_add_f32_e32 v70, v74, v70
	v_add_f32_e32 v71, v75, v71
	s_add_u32 s12, s20, s12
	v_fma_f32 v2, v2, v196, v70
	v_fma_f32 v3, v3, v197, v71
	s_addc_u32 s13, s21, s13
	v_add_f32_e32 v70, v166, v164
	v_add_f32_e32 v71, v167, v165
	v_add_f32_e32 v72, v142, v140
	v_add_f32_e32 v73, v143, v141
	s_add_u32 s10, s20, s10
	v_add_f32_e32 v70, v144, v70
	v_add_f32_e32 v71, v145, v71
	v_add_f32_e32 v72, v132, v72
	v_add_f32_e32 v73, v133, v73
	s_addc_u32 s11, s21, s11
	v_add_f32_e32 v70, v146, v70
	v_add_f32_e32 v71, v147, v71
	v_add_f32_e32 v72, v202, v72
	v_add_f32_e32 v73, v203, v73
	s_add_u32 s8, s20, s8
	v_mov_b32_e32 v74, v72
	v_mov_b32_e32 v75, v70
	v_mov_b32_e32 v70, v73
	s_addc_u32 s9, s21, s9
	v_mov_b32_e32 v135, v198
	v_add_f32_e32 v70, v74, v70
	v_add_f32_e32 v71, v75, v71
	s_add_u32 s6, s20, s6
	v_fma_f32 v186, v186, v134, v70
	v_fma_f32 v187, v187, v135, v71
	v_lshl_add_u64 v[70:71], v[192:193], 0, s[22:23]
	s_addc_u32 s7, s21, s7
	v_mad_u64_u32 v[144:145], s[22:23], s24, v226, v[70:71]
	v_lshl_add_u64 v[72:73], s[20:21], 0, v[68:69]
	v_lshl_add_u64 v[76:77], s[18:19], 0, v[68:69]
	v_lshl_add_u64 v[70:71], s[16:17], 0, v[68:69]
	v_lshl_add_u64 v[132:133], s[12:13], 0, v[68:69]
	v_lshl_add_u64 v[74:75], s[10:11], 0, v[68:69]
	v_lshl_add_u64 v[134:135], s[8:9], 0, v[68:69]
	v_lshl_add_u64 v[68:69], s[6:7], 0, v[68:69]
	s_add_i32 m0, s28, 4096
	s_nop 0
	global_load_lds_dwordx4 v[72:73], off
	s_add_i32 m0, s28, 5120
	s_nop 0
	global_load_lds_dwordx4 v[76:77], off
	s_add_i32 m0, s28, 6144
	s_nop 0
	global_load_lds_dwordx4 v[132:133], off
	s_add_i32 m0, s28, 7168
	s_nop 0
	global_load_lds_dwordx4 v[134:135], off
	v_add_co_u32_e32 v136, vcc, 0xa000, v144
	s_nop 1
	v_addc_co_u32_e32 v137, vcc, 0, v145, vcc
	s_add_i32 m0, s28, -576
	s_nop 0
	global_load_lds_dwordx4 v[136:137], off offset:3648
	s_add_i32 m0, s28, -1536
	s_nop 0
	global_load_lds_dwordx4 v[136:137], off offset:3584
	s_add_i32 m0, s28, -2624
	s_nop 0
	global_load_lds_dwordx4 v[144:145], off offset:3648
	s_add_i32 m0, s28, -3584
	s_nop 0
	global_load_lds_dwordx4 v[144:145], off offset:3584
	s_andn2_b64 vcc, exec, s[34:35]
	s_cbranch_vccnz .LBB0_164
	s_waitcnt vmcnt(8)
	ds_read_b128 v[156:159], v216 offset:8192
	ds_read_b128 v[160:163], v216 offset:9216
	ds_read_b128 v[152:155], v216 offset:10240
	ds_read_b128 v[148:151], v216 offset:11264
	ds_read_b128 v[112:115], v216 offset:12288
	ds_read_b128 v[108:111], v216 offset:13312
	ds_read_b128 v[104:107], v216 offset:14336
	ds_read_b128 v[92:95], v216 offset:15360
	s_waitcnt lgkmcnt(4)
	v_mfma_f32_16x16x32_bf16 v[164:167], v[156:159], v[20:23], 0
	s_add_i32 s44, s44, -7
	s_cmp_lt_u32 s44, -4
	s_cselect_b64 s[6:7], -1, 0
	s_waitcnt vmcnt(10)
	v_mfma_f32_16x16x32_bf16 v[180:183], v[160:163], v[24:27], v[164:167]
	s_cmp_lt_u32 s42, s40
	s_cselect_b64 s[8:9], -1, 0
	s_and_b64 s[6:7], s[8:9], s[6:7]
	v_mfma_f32_16x16x32_bf16 v[164:167], v[156:159], v[28:31], 0
	s_andn2_b64 vcc, exec, s[6:7]
	v_mfma_f32_16x16x32_bf16 v[172:175], v[160:163], v[32:35], v[164:167]
	v_mfma_f32_16x16x32_bf16 v[164:167], v[156:159], v[36:39], 0
	v_mfma_f32_16x16x32_bf16 v[156:159], v[156:159], v[44:47], 0
	v_mfma_f32_16x16x32_bf16 v[168:171], v[160:163], v[40:43], v[164:167]
	v_mfma_f32_16x16x32_bf16 v[156:159], v[160:163], v[48:51], v[156:159]
	s_waitcnt vmcnt(9)
	v_mfma_f32_16x16x32_bf16 v[160:163], v[152:155], v[20:23], 0
	s_waitcnt vmcnt(8)
	v_mfma_f32_16x16x32_bf16 v[176:179], v[148:151], v[24:27], v[160:163]
	v_mfma_f32_16x16x32_bf16 v[160:163], v[152:155], v[28:31], 0
	v_mfma_f32_16x16x32_bf16 v[164:167], v[152:155], v[36:39], 0
	v_mfma_f32_16x16x32_bf16 v[152:155], v[152:155], v[44:47], 0
	v_mfma_f32_16x16x32_bf16 v[160:163], v[148:151], v[32:35], v[160:163]
	v_mfma_f32_16x16x32_bf16 v[164:167], v[148:151], v[40:43], v[164:167]
	v_mfma_f32_16x16x32_bf16 v[152:155], v[148:151], v[48:51], v[152:155]
	s_cbranch_vccnz .LBB0_163
	v_add_u32_e32 v148, 80, v207
	v_cmp_gt_u32_e64 s[6:7], s93, v148
	v_add_u32_e32 v148, 81, v207
	v_cmp_gt_u32_e64 s[8:9], s93, v148
	v_add_u32_e32 v148, 82, v207
	v_cmp_gt_u32_e64 s[10:11], s93, v148
	v_add_u32_e32 v148, 83, v207
	v_cmp_gt_u32_e64 s[12:13], s93, v148
	s_nop 1
	v_cndmask_b32_e64 v180, v180, v227, s[6:7]
	v_cndmask_b32_e64 v181, v181, v227, s[8:9]
	v_cndmask_b32_e64 v182, v182, v227, s[10:11]
	v_cndmask_b32_e64 v183, v183, v227, s[12:13]
	v_add_u32_e32 v148, 64, v207
	v_cmp_gt_u32_e64 s[6:7], s93, v148
	v_add_u32_e32 v148, 65, v207
	v_cmp_gt_u32_e64 s[8:9], s93, v148
	v_add_u32_e32 v148, 66, v207
	v_cmp_gt_u32_e64 s[10:11], s93, v148
	v_add_u32_e32 v148, 67, v207
	v_cmp_gt_u32_e64 s[12:13], s93, v148
	s_nop 1
	v_cndmask_b32_e64 v172, v172, v227, s[6:7]
	v_cndmask_b32_e64 v173, v173, v227, s[8:9]
	v_cndmask_b32_e64 v174, v174, v227, s[10:11]
	v_cndmask_b32_e64 v175, v175, v227, s[12:13]
	v_add_u32_e32 v148, 48, v207
	v_cmp_gt_u32_e64 s[6:7], s93, v148
	v_add_u32_e32 v148, 49, v207
	v_cmp_gt_u32_e64 s[8:9], s93, v148
	v_add_u32_e32 v148, 50, v207
	v_cmp_gt_u32_e64 s[10:11], s93, v148
	v_add_u32_e32 v148, 51, v207
	v_cmp_gt_u32_e64 s[12:13], s93, v148
	s_nop 1
	v_cndmask_b32_e64 v168, v168, v227, s[6:7]
	v_cndmask_b32_e64 v169, v169, v227, s[8:9]
	v_cndmask_b32_e64 v170, v170, v227, s[10:11]
	v_cndmask_b32_e64 v171, v171, v227, s[12:13]
	v_add_u32_e32 v148, 32, v207
	v_cmp_gt_u32_e64 s[6:7], s93, v148
	v_add_u32_e32 v148, 33, v207
	v_cmp_gt_u32_e64 s[8:9], s93, v148
	v_add_u32_e32 v148, 34, v207
	v_cmp_gt_u32_e64 s[10:11], s93, v148
	v_add_u32_e32 v148, 35, v207
	v_cmp_gt_u32_e64 s[12:13], s93, v148
	s_nop 1
	v_cndmask_b32_e64 v156, v156, v227, s[6:7]
	v_cndmask_b32_e64 v157, v157, v227, s[8:9]
	v_cndmask_b32_e64 v158, v158, v227, s[10:11]
	v_cndmask_b32_e64 v159, v159, v227, s[12:13]
	v_add_u32_e32 v148, 84, v207
	v_cmp_gt_u32_e64 s[6:7], s93, v148
	v_add_u32_e32 v148, 85, v207
	v_cmp_gt_u32_e64 s[8:9], s93, v148
	v_add_u32_e32 v148, 86, v207
	v_cmp_gt_u32_e64 s[10:11], s93, v148
	v_add_u32_e32 v148, 87, v207
	v_cmp_gt_u32_e64 s[12:13], s93, v148
	s_nop 1
	v_cndmask_b32_e64 v176, v176, v227, s[6:7]
	v_cndmask_b32_e64 v177, v177, v227, s[8:9]
	v_cndmask_b32_e64 v178, v178, v227, s[10:11]
	v_cndmask_b32_e64 v179, v179, v227, s[12:13]
	v_add_u32_e32 v148, 68, v207
	v_cmp_gt_u32_e64 s[6:7], s93, v148
	v_add_u32_e32 v148, 69, v207
	v_cmp_gt_u32_e64 s[8:9], s93, v148
	v_add_u32_e32 v148, 70, v207
	v_cmp_gt_u32_e64 s[10:11], s93, v148
	v_add_u32_e32 v148, 71, v207
	v_cmp_gt_u32_e64 s[12:13], s93, v148
	s_nop 1
	v_cndmask_b32_e64 v160, v160, v227, s[6:7]
	v_cndmask_b32_e64 v161, v161, v227, s[8:9]
	v_cndmask_b32_e64 v162, v162, v227, s[10:11]
	v_cndmask_b32_e64 v163, v163, v227, s[12:13]
	v_add_u32_e32 v148, 52, v207
	v_cmp_gt_u32_e64 s[6:7], s93, v148
	v_add_u32_e32 v148, 53, v207
	v_cmp_gt_u32_e64 s[8:9], s93, v148
	v_add_u32_e32 v148, 54, v207
	v_cmp_gt_u32_e64 s[10:11], s93, v148
	v_add_u32_e32 v148, 55, v207
	v_cmp_gt_u32_e64 s[12:13], s93, v148
	s_nop 1
	v_cndmask_b32_e64 v164, v164, v227, s[6:7]
	v_cndmask_b32_e64 v165, v165, v227, s[8:9]
	v_cndmask_b32_e64 v166, v166, v227, s[10:11]
	v_cndmask_b32_e64 v167, v167, v227, s[12:13]
	v_add_u32_e32 v148, 36, v207
	v_cmp_gt_u32_e64 s[6:7], s93, v148
	v_add_u32_e32 v148, 37, v207
	v_cmp_gt_u32_e64 s[8:9], s93, v148
	v_add_u32_e32 v148, 38, v207
	v_cmp_gt_u32_e64 s[10:11], s93, v148
	v_add_u32_e32 v148, 39, v207
	v_cmp_gt_u32_e64 s[12:13], s93, v148
	s_nop 1
	v_cndmask_b32_e64 v152, v152, v227, s[6:7]
	v_cndmask_b32_e64 v153, v153, v227, s[8:9]
	v_cndmask_b32_e64 v154, v154, v227, s[10:11]
	v_cndmask_b32_e64 v155, v155, v227, s[12:13]
.LBB0_163:
	v_max_f32_e32 v148, v180, v181
	v_max_f32_e32 v149, v182, v183
	v_max_f32_e32 v150, v178, v179
	v_max3_f32 v150, v176, v177, v150
	v_max3_f32 v148, v148, v149, v150
	ds_bpermute_b32 v149, v199, v148
	s_waitcnt lgkmcnt(0)
	v_max_f32_e32 v148, v148, v149
	ds_bpermute_b32 v149, v195, v148
	s_waitcnt lgkmcnt(0)
	v_max3_f32 v194, v206, v148, v149
	v_sub_f32_e32 v148, v180, v194
	v_sub_f32_e32 v149, v181, v194
	v_sub_f32_e32 v180, v182, v194
	v_sub_f32_e32 v181, v183, v194
	v_exp_f32_e32 v148, v148
	v_exp_f32_e32 v149, v149
	v_exp_f32_e32 v180, v180
	v_exp_f32_e32 v181, v181
	v_sub_f32_e32 v176, v176, v194
	v_sub_f32_e32 v177, v177, v194
	v_sub_f32_e32 v178, v178, v194
	v_sub_f32_e32 v179, v179, v194
	v_exp_f32_e32 v176, v176
	v_exp_f32_e32 v177, v177
	v_exp_f32_e32 v178, v178
	v_exp_f32_e32 v179, v179
	v_add_f32_e32 v150, 0, v148
	v_add_f32_e32 v151, 0, v149
	v_cvt_pk_bf16_f32 v148, v148, v149
	v_cvt_pk_bf16_f32 v149, v180, v181
	v_sub_f32_e32 v196, v206, v194
	v_add_f32_e32 v150, v180, v150
	v_add_f32_e32 v151, v181, v151
	v_exp_f32_e32 v198, v196
	v_add_f32_e32 v150, v176, v150
	v_add_f32_e32 v151, v177, v151
	v_mov_b32_e32 v181, v198
	v_add_f32_e32 v182, v178, v150
	v_add_f32_e32 v183, v179, v151
	v_cvt_pk_bf16_f32 v150, v176, v177
	v_cvt_pk_bf16_f32 v151, v178, v179
	v_max_f32_e32 v176, v172, v173
	v_max_f32_e32 v177, v174, v175
	v_max_f32_e32 v178, v162, v163
	v_max3_f32 v178, v160, v161, v178
	v_max3_f32 v176, v176, v177, v178
	ds_bpermute_b32 v177, v199, v176
	v_mul_f32_e32 v130, v130, v198
	v_mul_f32_e32 v131, v131, v198
	v_mul_f32_e32 v128, v128, v198
	v_mul_f32_e32 v129, v129, v198
	v_mul_f32_e32 v118, v118, v198
	v_mul_f32_e32 v119, v119, v198
	v_mul_f32_e32 v116, v116, v198
	v_mul_f32_e32 v117, v117, v198
	s_waitcnt lgkmcnt(0)
	v_max_f32_e32 v176, v176, v177
	ds_bpermute_b32 v177, v195, v176
	v_mul_f32_e32 v122, v122, v198
	v_mul_f32_e32 v123, v123, v198
	v_mul_f32_e32 v120, v120, v198
	v_mul_f32_e32 v121, v121, v198
	v_mul_f32_e32 v126, v126, v198
	v_mul_f32_e32 v127, v127, v198
	v_mul_f32_e32 v124, v124, v198
	v_mul_f32_e32 v125, v125, v198
	s_waitcnt lgkmcnt(0)
	v_max3_f32 v196, v204, v176, v177
	v_sub_f32_e32 v172, v172, v196
	v_sub_f32_e32 v173, v173, v196
	v_sub_f32_e32 v174, v174, v196
	v_sub_f32_e32 v175, v175, v196
	v_exp_f32_e32 v172, v172
	v_exp_f32_e32 v173, v173
	v_exp_f32_e32 v174, v174
	v_exp_f32_e32 v175, v175
	v_sub_f32_e32 v160, v160, v196
	v_sub_f32_e32 v161, v161, v196
	v_exp_f32_e32 v178, v160
	v_exp_f32_e32 v179, v161
	v_add_f32_e32 v176, v174, v172
	v_add_f32_e32 v177, v175, v173
	v_sub_f32_e32 v162, v162, v196
	v_sub_f32_e32 v163, v163, v196
	v_sub_f32_e32 v180, v204, v196
	v_add_f32_e32 v160, v178, v176
	v_add_f32_e32 v161, v179, v177
	v_exp_f32_e32 v176, v162
	v_exp_f32_e32 v177, v163
	v_exp_f32_e32 v180, v180
	v_mov_b32_e32 v163, v182
	v_mfma_f32_16x16x32_bf16 v[128:131], v[112:115], v[148:151], v[128:131]
	v_add_f32_e64 v160, v176, v160
	v_add_f32_e64 v161, v177, v161
	v_mul_f32_e32 v98, v98, v180
	v_mul_f32_e32 v99, v99, v180
	v_mov_b32_e32 v162, v160
	v_mov_b32_e32 v182, v161
	v_add_f32_e32 v160, v162, v182
	v_add_f32_e32 v161, v163, v183
	v_mul_f32_e32 v96, v96, v180
	v_mul_f32_e32 v97, v97, v180
	v_fma_f32 v2, v2, v180, v160
	v_fma_f32 v3, v3, v181, v161
	v_cvt_pk_bf16_f32 v160, v172, v173
	v_cvt_pk_bf16_f32 v161, v174, v175
	v_max_f32_e32 v172, v168, v169
	v_max_f32_e32 v173, v170, v171
	v_max_f32_e32 v174, v166, v167
	v_max3_f32 v174, v164, v165, v174
	v_max3_f32 v172, v172, v173, v174
	ds_bpermute_b32 v173, v199, v172
	v_cvt_pk_bf16_f32 v162, v178, v179
	v_cvt_pk_bf16_f32 v163, v176, v177
	v_mul_f32_e32 v82, v82, v180
	v_mul_f32_e32 v83, v83, v180
	v_mul_f32_e32 v80, v80, v180
	v_mul_f32_e32 v81, v81, v180
	s_waitcnt lgkmcnt(0)
	v_max_f32_e32 v172, v172, v173
	ds_bpermute_b32 v173, v195, v172
	v_mul_f32_e32 v90, v90, v180
	v_mul_f32_e32 v91, v91, v180
	v_mul_f32_e32 v88, v88, v180
	v_mul_f32_e32 v89, v89, v180
	v_mul_f32_e32 v102, v102, v180
	v_mul_f32_e32 v103, v103, v180
	v_mul_f32_e32 v100, v100, v180
	v_mul_f32_e32 v101, v101, v180
	s_waitcnt lgkmcnt(0)
	v_max3_f32 v198, v200, v172, v173
	v_sub_f32_e32 v168, v168, v198
	v_sub_f32_e32 v169, v169, v198
	v_sub_f32_e32 v170, v170, v198
	v_sub_f32_e32 v171, v171, v198
	v_exp_f32_e32 v168, v168
	v_exp_f32_e32 v169, v169
	v_exp_f32_e32 v170, v170
	v_exp_f32_e32 v171, v171
	v_sub_f32_e32 v164, v164, v198
	v_sub_f32_e32 v165, v165, v198
	v_exp_f32_e32 v174, v164
	v_exp_f32_e32 v175, v165
	v_add_f32_e32 v172, v170, v168
	v_add_f32_e32 v173, v171, v169
	v_sub_f32_e32 v166, v166, v198
	v_sub_f32_e32 v167, v167, v198
	v_sub_f32_e32 v178, v200, v198
	v_add_f32_e32 v164, v174, v172
	v_add_f32_e32 v165, v175, v173
	v_exp_f32_e32 v172, v166
	v_exp_f32_e32 v173, v167
	v_exp_f32_e32 v178, v178
	v_mfma_f32_16x16x32_bf16 v[96:99], v[112:115], v[160:163], v[96:99]
	v_add_f32_e64 v176, v172, v164
	v_add_f32_e64 v177, v173, v165
	v_cvt_pk_bf16_f32 v164, v168, v169
	v_cvt_pk_bf16_f32 v165, v170, v171
	v_max_f32_e32 v168, v156, v157
	v_max_f32_e32 v169, v158, v159
	v_max_f32_e32 v170, v154, v155
	v_max3_f32 v170, v152, v153, v170
	v_max3_f32 v168, v168, v169, v170
	ds_bpermute_b32 v169, v199, v168
	v_cvt_pk_bf16_f32 v166, v174, v175
	v_cvt_pk_bf16_f32 v167, v172, v173
	v_mov_b32_e32 v173, v178
	v_mul_f32_e32 v58, v58, v178
	v_mul_f32_e32 v59, v59, v178
	s_waitcnt lgkmcnt(0)
	v_max_f32_e32 v168, v168, v169
	ds_bpermute_b32 v169, v195, v168
	v_mul_f32_e32 v56, v56, v178
	v_mul_f32_e32 v57, v57, v178
	v_mul_f32_e32 v54, v54, v178
	v_mul_f32_e32 v55, v55, v178
	v_mul_f32_e32 v52, v52, v178
	v_mul_f32_e32 v53, v53, v178
	v_mul_f32_e32 v62, v62, v178
	v_mul_f32_e32 v63, v63, v178
	s_waitcnt lgkmcnt(0)
	v_max3_f32 v202, v0, v168, v169
	v_sub_f32_e32 v156, v156, v202
	v_sub_f32_e32 v157, v157, v202
	v_sub_f32_e32 v158, v158, v202
	v_sub_f32_e32 v159, v159, v202
	v_exp_f32_e32 v156, v156
	v_exp_f32_e32 v157, v157
	v_exp_f32_e32 v158, v158
	v_exp_f32_e32 v159, v159
	v_sub_f32_e32 v152, v152, v202
	v_sub_f32_e32 v153, v153, v202
	v_exp_f32_e32 v170, v152
	v_exp_f32_e32 v171, v153
	v_add_f32_e32 v168, v158, v156
	v_add_f32_e32 v169, v159, v157
	v_sub_f32_e32 v154, v154, v202
	v_sub_f32_e32 v155, v155, v202
	v_sub_f32_e32 v0, v0, v202
	v_add_f32_e32 v152, v170, v168
	v_add_f32_e32 v153, v171, v169
	v_exp_f32_e32 v168, v154
	v_exp_f32_e32 v169, v155
	v_exp_f32_e32 v172, v0
	v_mov_b32_e32 v155, v176
	v_mul_f32_e32 v60, v60, v178
	v_mul_f32_e32 v61, v61, v178
	v_add_f32_e32 v152, v168, v152
	v_add_f32_e32 v153, v169, v153
	v_mul_f32_e32 v66, v66, v178
	v_mul_f32_e32 v67, v67, v178
	v_mov_b32_e32 v154, v152
	v_mov_b32_e32 v176, v153
	v_mul_f32_e32 v64, v64, v178
	v_mul_f32_e32 v65, v65, v178
	v_add_f32_e32 v152, v154, v176
	v_add_f32_e32 v153, v155, v177
	v_mul_f32_e32 v6, v6, v172
	v_mul_f32_e32 v7, v7, v172
	v_mul_f32_e32 v4, v4, v172
	v_mul_f32_e32 v5, v5, v172
	v_mul_f32_e32 v10, v10, v172
	v_mul_f32_e32 v11, v11, v172
	v_mul_f32_e32 v8, v8, v172
	v_mul_f32_e32 v9, v9, v172
	v_mul_f32_e32 v14, v14, v172
	v_mul_f32_e32 v15, v15, v172
	v_mul_f32_e32 v12, v12, v172
	v_mul_f32_e32 v13, v13, v172
	v_mul_f32_e32 v18, v18, v172
	v_mul_f32_e32 v19, v19, v172
	v_mul_f32_e32 v16, v16, v172
	v_mul_f32_e32 v17, v17, v172
	v_fma_f32 v186, v186, v172, v152
	v_fma_f32 v187, v187, v173, v153
	v_cvt_pk_bf16_f32 v152, v156, v157
	v_cvt_pk_bf16_f32 v153, v158, v159
	v_cvt_pk_bf16_f32 v154, v170, v171
	v_cvt_pk_bf16_f32 v155, v168, v169
	v_mfma_f32_16x16x32_bf16 v[56:59], v[112:115], v[164:167], v[56:59]
	s_nop 0
	v_mfma_f32_16x16x32_bf16 v[4:7], v[112:115], v[152:155], v[4:7]
	v_mfma_f32_16x16x32_bf16 v[116:119], v[108:111], v[148:151], v[116:119]
	v_mfma_f32_16x16x32_bf16 v[80:83], v[108:111], v[160:163], v[80:83]
	v_mfma_f32_16x16x32_bf16 v[52:55], v[108:111], v[164:167], v[52:55]
	v_mfma_f32_16x16x32_bf16 v[8:11], v[108:111], v[152:155], v[8:11]
	v_mfma_f32_16x16x32_bf16 v[120:123], v[104:107], v[148:151], v[120:123]
	v_mfma_f32_16x16x32_bf16 v[88:91], v[104:107], v[160:163], v[88:91]
	v_mfma_f32_16x16x32_bf16 v[60:63], v[104:107], v[164:167], v[60:63]
	v_mfma_f32_16x16x32_bf16 v[12:15], v[104:107], v[152:155], v[12:15]
	v_mfma_f32_16x16x32_bf16 v[124:127], v[92:95], v[148:151], v[124:127]
	v_mfma_f32_16x16x32_bf16 v[100:103], v[92:95], v[160:163], v[100:103]
	v_mfma_f32_16x16x32_bf16 v[64:67], v[92:95], v[164:167], v[64:67]
	v_mfma_f32_16x16x32_bf16 v[16:19], v[92:95], v[152:155], v[16:19]
	s_andn2_b64 vcc, exec, s[96:97]
	s_cbranch_vccnz .LBB0_165
	s_branch .LBB0_139
